# grid barrier: XCC group counters count monotonically (no reset atomic on the last arriver's path), generation in a spill lane, early L1 invalidate
# baseline (speedup 1.0000x reference)
; __device__ __forceinline__ int ltid() { return launder((int)threadIdx.x); }
; __device__ __forceinline__ void prologue(const Params& P) {
;   unsigned char* ws = P.ws; const int tid = ltid();
;   if (blockIdx.x == 0 && tid < 64) {
;     unsigned* ctl = (unsigned*)(ws + WS_CTL);
;     if (tid < 8 || (tid >= 16 && tid < 48)) ctl[tid] = 0u;
; __global__ void __launch_bounds__(512) mega(Params P) {
;   cg::grid_group grid = cg::this_grid();
;   unsigned char* ws = P.ws;
;   if (EN & 1) prologue(P);
;   grid.sync();
_Z4mega6Params:
	s_mov_b32 s96, 0
	v_writelane_b32 v255, s96, 20
	v_writelane_b32 v255, s96, 25
	s_mov_b32 s96, 1
	v_writelane_b32 v255, s96, 24
	s_load_dwordx16 s[4:19], s[0:1], 0x40
	s_add_u32 s56, s0, 0xa0
	s_load_dword s52, s[0:1], 0xa0
	s_addc_u32 s57, s1, 0
	v_and_b32_e32 v155, 0x3ff, v0
	s_waitcnt lgkmcnt(0)
	v_writelane_b32 v253, s4, 0
	v_mov_b32_e32 v4, v155
	s_cmp_eq_u32 s2, 0
	v_writelane_b32 v253, s5, 1
	v_writelane_b32 v253, s6, 2
	v_writelane_b32 v253, s7, 3
	v_writelane_b32 v253, s8, 4
	v_writelane_b32 v253, s9, 5
	v_writelane_b32 v253, s10, 6
	v_writelane_b32 v253, s11, 7
	v_writelane_b32 v253, s12, 8
	v_writelane_b32 v253, s13, 9
	v_writelane_b32 v253, s14, 10
	v_writelane_b32 v253, s15, 11
	v_writelane_b32 v253, s16, 12
	v_writelane_b32 v253, s17, 13
	v_writelane_b32 v253, s18, 14
	v_writelane_b32 v253, s19, 15
	s_load_dwordx8 s[4:11], s[0:1], 0x80
	s_mov_b32 s37, s2
	s_cselect_b64 s[2:3], -1, 0
	v_cmp_gt_i32_e32 vcc, 64, v4
	s_waitcnt lgkmcnt(0)
	v_writelane_b32 v253, s4, 16
	s_and_b64 s[2:3], s[2:3], vcc
	s_nop 0
	v_writelane_b32 v253, s5, 17
	v_writelane_b32 v253, s6, 18
	v_writelane_b32 v253, s7, 19
	v_writelane_b32 v253, s8, 20
	v_writelane_b32 v253, s9, 21
	v_writelane_b32 v253, s10, 22
	v_writelane_b32 v253, s11, 23
	s_and_saveexec_b64 s[4:5], s[2:3]
	s_cbranch_execz .LBB0_15
	v_add_u32_e32 v1, -16, v4
	v_cmp_lt_i32_e32 vcc, 7, v4
	v_cmp_lt_u32_e64 s[2:3], 31, v1
	s_and_b64 s[2:3], vcc, s[2:3]
	v_mov_b32_e32 v5, 0
	s_and_saveexec_b64 s[6:7], s[2:3]
	s_xor_b64 s[2:3], exec, s[6:7]
	s_or_saveexec_b64 s[2:3], s[2:3]
	v_mov_b64_e32 v[6:7], v[4:5]
	s_xor_b64 exec, exec, s[2:3]
	s_cbranch_execz .LBB0_3
	s_load_dwordx8 s[8:15], s[0:1], 0x80
	v_ashrrev_i32_e32 v7, 31, v4
	v_mov_b32_e32 v6, v4
	v_mov_b32_e32 v1, 0
	s_waitcnt lgkmcnt(0)
	v_lshl_add_u64 v[2:3], v[6:7], 2, s[14:15]
	global_store_dword v[2:3], v1, off

; __global__ void __launch_bounds__(512) mega(Params P) {
;     ...
;   grid.sync();
.Lgbx_arr_0:
	s_lshl_b32 s1, s1, 2
	s_addk_i32 s1, 0x88
	v_mov_b32_e32 v2, s1
	v_readlane_b32 s98, v255, 20
	s_nop 3
	s_lshl_b32 s99, s98, 16
	v_mov_b32_e32 v0, s99
	s_add_i32 s98, s98, 1
	v_writelane_b32 v255, s98, 20
	v_mov_b32_e32 v3, 1
	global_atomic_add v3, v2, v3, s[4:5] sc0
	s_waitcnt vmcnt(0)
	buffer_inv sc1
	v_readfirstlane_b32 s1, v3
	s_nop 3
	s_cmp_eq_u32 s96, 0
	s_cbranch_scc1 .Lgbx_cn_0
	s_and_b32 s1, s1, 0xffff
	s_add_i32 s0, s6, -1
	s_cmp_lg_u32 s1, s0
	s_cbranch_scc1 .Lgbx_poll_0
	s_sub_i32 s1, 0x10000, s6
	v_mov_b32_e32 v3, s1
	global_atomic_add v3, v2, v3, s[4:5] sc0
	s_waitcnt vmcnt(0)
	s_branch .Lgbx_top_0
.Lgbx_cn_0:
	v_readlane_b32 s98, v255, 25
	s_nop 3
	s_add_i32 s99, s98, 1
	v_writelane_b32 v255, s99, 25
	s_mul_i32 s0, s6, s99
	s_add_i32 s0, s0, 0xffff
	s_cmp_lg_u32 s1, s0
	s_cbranch_scc1 .Lgbx_poll_0
	buffer_wbl2 sc1
	s_waitcnt vmcnt(0)
.Lgbx_top_0:
	v_mov_b32_e32 v3, 1
	global_atomic_add v3, v1, v3, s[4:5] sc0
	s_waitcnt vmcnt(0)
	v_and_b32_e32 v3, 0xffff, v3
	s_nop 0
	v_readfirstlane_b32 s1, v3
	s_nop 3
	s_add_i32 s0, s7, -1
	s_cmp_lg_u32 s1, s0
	s_cbranch_scc1 .Lgbx_poll_0
	s_sub_i32 s1, 0x10000, s7
	v_mov_b32_e32 v3, s1
	global_atomic_add v1, v3, s[4:5]

; __global__ void __launch_bounds__(512) mega(Params P) {
;     ...
;   for (int l = 0; l < 2; ++l) {
;     if (l > 0) { norm_phase(H, P.attn_norm + l * DM, HN); grid.sync(); }
;     { EpiIn e; e.cqkv = CQKV; e.ka = (bf16_t*)(ws + WS_KA); e.qd = (bf16_t*)(ws + WS_QD); e.kd = (bf16_t*)(ws + WS_KD); e.vtd = (bf16_t*)(ws + WS_VTD);
;       e.qs = (bf16_t*)(ws + WS_QS); e.ks = (bf16_t*)(ws + WS_KS); e.vts = (bf16_t*)(ws + WS_VTS); e.rope = rope;
;       if (EN & 2) gemm_phase(HN, DM, (const bf16_t*)(ws + WS_WIN) + (size_t)l * N_IN * 1024, 1024, NREAL, N_IN, 1024, e); }
;     grid.sync();
;     { EpiUp e; e.qa = (bf16_t*)(ws + WS_QA); e.ka = (bf16_t*)(ws + WS_KA); e.vta = (bf16_t*)(ws + WS_VTA); e.rope = rope; e.brow = 0; e.rs_direct = 0.f; e.use_direct = 0;
;       if (EN & 4) up_phase(CQKV, (const bf16_t*)(ws + WS_WQB) + (size_t)l * 768 * 256, (const bf16_t*)(ws + WS_WKVB) + (size_t)l * 768 * 256, e); }
;     grid.sync();
;     attn_phase(P, l);
;     grid.sync();
;     if (l == 0) { EpiResid0 e; e.H = H; e.xsrc = P.x; e.msrc = P.meta; gemm_phase(HN, DM, (const bf16_t*)(ws + WS_WOUT), 1024, NREAL, 1024, 1024, e); }
;     else { EpiResid e; e.H = H; gemm_phase(HN, DM, (const bf16_t*)(ws + WS_WOUT) + (size_t)l * 1024 * 1024, 1024, NREAL, 1024, 1024, e); }
;     grid.sync();
;     norm_phase(H, P.ffn_norm + l * DM, HN);
;     grid.sync();
;     if (EN & 128) { EpiGU e; e.act = (bf16_t*)(ws + WS_ACT); gemm_phase(HN, DM, (const bf16_t*)(ws + WS_WGU) + (size_t)l * N_GU * 1024, 1024, NREAL, N_GU, 1024, e); }
;     grid.sync();
;     if (EN & 256) { EpiResid e; e.H = H; gemm_phase((const bf16_t*)(ws + WS_ACT), DFF, (const bf16_t*)(ws + WS_WDN) + (size_t)l * 1024 * DFF, DFF, NREAL, 1024, DFF, e); }
;     grid.sync();
.Lgbx_arr_4:
	s_lshl_b32 s1, s1, 2
	s_addk_i32 s1, 0x88
	v_mov_b32_e32 v2, s1
	v_readlane_b32 s98, v255, 20
	s_nop 3
	s_lshl_b32 s99, s98, 16
	v_mov_b32_e32 v0, s99
	s_add_i32 s98, s98, 1
	v_writelane_b32 v255, s98, 20
	v_mov_b32_e32 v3, 1
	global_atomic_add v3, v2, v3, s[6:7] sc0
	s_waitcnt vmcnt(0)
	buffer_inv sc1
	v_readfirstlane_b32 s1, v3
	s_nop 3
	s_cmp_eq_u32 s96, 0
	s_cbranch_scc1 .Lgbx_cn_4
	s_and_b32 s1, s1, 0xffff
	s_add_i32 s0, s8, -1
	s_cmp_lg_u32 s1, s0
	s_cbranch_scc1 .Lgbx_poll_4
	s_sub_i32 s1, 0x10000, s8
	v_mov_b32_e32 v3, s1
	global_atomic_add v3, v2, v3, s[6:7] sc0
	s_waitcnt vmcnt(0)
	s_branch .Lgbx_top_4
.Lgbx_cn_4:
	v_readlane_b32 s98, v255, 25
	s_nop 3
	s_add_i32 s99, s98, 1
	v_writelane_b32 v255, s99, 25
	s_mul_i32 s0, s8, s99
	s_add_i32 s0, s0, 0xffff
	s_cmp_lg_u32 s1, s0
	s_cbranch_scc1 .Lgbx_poll_4
	buffer_wbl2 sc1
	s_waitcnt vmcnt(0)
.Lgbx_top_4:
	v_mov_b32_e32 v3, 1
	global_atomic_add v3, v1, v3, s[6:7] sc0
	s_waitcnt vmcnt(0)
	v_and_b32_e32 v3, 0xffff, v3
	s_nop 0
	v_readfirstlane_b32 s1, v3
	s_nop 3
	s_add_i32 s0, s9, -1
	s_cmp_lg_u32 s1, s0
	s_cbranch_scc1 .Lgbx_poll_4
	s_sub_i32 s1, 0x10000, s9
	v_mov_b32_e32 v3, s1
	global_atomic_add v1, v3, s[6:7]
